# conf LayerNorm wave sums via DPP, hgrn lower-bound logits loaded with 8 wide loads up front
# speedup vs baseline: 1.0328x; 1.0027x over previous
; #define LAS __attribute__((address_space(3)))
; __device__ __forceinline__ unsigned pk2(float lo, float hi) { return pg8::cvt_pk_bf16(lo, hi); }
; __device__ __forceinline__ float silu_acc(float x) { return x * frcp(1.0f + fexp(-x)); }
; __device__ __forceinline__ void conf_unit(const Ctx& X, LAS unsigned char* lds, int b, int c, int tid, int wave, int lane, int layer) {
;     ...
;     {
;         const f32x4 lw = *((const f32x4*)(X.in[6] + layer * 256) + lane), lb = *((const f32x4*)(X.in[7] + layer * 256) + lane);
; #pragma unroll 2
;         for (int tk = wave * 8; tk < wave * 8 + 8; ++tk) {
;             const f32x4 v = *((const LAS f32x4*)(Y + tk * 256) + lane);
;             const float mu = wave_sum((v.x + v.y) + (v.z + v.w)) * (1.f / 256.f);
;             const f32x4 dv = v - mu;
;             const float var = wave_sum((dv.x * dv.x + dv.y * dv.y) + (dv.z * dv.z + dv.w * dv.w)) * (1.f / 256.f);
;             const float rs = rsqrtf(var + 1e-5f);
;             f32x4 o = dv * rs * lw + lb;
;             const bool on = (MIX_MASK & 2) != 0;
;             u32x2 p; p.x = on ? pk2(silu_acc(o.x), silu_acc(o.y)) : 0u; p.y = on ? pk2(silu_acc(o.z), silu_acc(o.w)) : 0u;
;             *(u32x2*)(mix + ((size_t)b * T + t0 + tk) * D + 256 + lane * 4) = p;
;         }
;     }
.LBB0_262:
	v_add_u32_e32 v23, s0, v22
	ds_read_b128 v[24:27], v23
	s_addk_i32 s0, 0x800
	s_cmpk_lg_i32 s0, 0x2000
	s_waitcnt lgkmcnt(0)
	v_mov_b32_e32 v28, v25
	v_mov_b32_e32 v29, v26
	v_mov_b32_e32 v30, v24
	v_mov_b32_e32 v31, v27
	v_pk_add_f32 v[28:29], v[28:29], v[30:31]
	s_nop 0
	v_add_f32_e32 v28, v28, v29
	s_nop 1
	v_add_f32_dpp v28, v28, v28 quad_perm:[1,0,3,2] row_mask:0xf bank_mask:0xf
	s_nop 1
	v_add_f32_dpp v28, v28, v28 quad_perm:[2,3,0,1] row_mask:0xf bank_mask:0xf
	s_nop 1
	v_add_f32_dpp v28, v28, v28 row_half_mirror row_mask:0xf bank_mask:0xf
	s_nop 1
	v_add_f32_dpp v28, v28, v28 row_mirror row_mask:0xf bank_mask:0xf
	s_nop 1
	v_add_f32_dpp v28, v28, v28 row_bcast:15 row_mask:0xa bank_mask:0xf
	s_nop 1
	v_add_f32_dpp v28, v28, v28 row_bcast:31 row_mask:0xc bank_mask:0xf
	s_nop 0
	v_readlane_b32 s98, v28, 63
	s_nop 3
	v_mov_b32_e32 v28, s98
	v_fmamk_f32 v25, v28, 0xbb800000, v25
	v_fmamk_f32 v24, v28, 0xbb800000, v24
	v_fmamk_f32 v27, v28, 0xbb800000, v27
	v_fmac_f32_e32 v26, 0xbb800000, v28
	v_pk_mul_f32 v[28:29], v[26:27], v[26:27]
	v_pk_mul_f32 v[30:31], v[24:25], v[24:25]
	s_nop 0
	v_pk_mov_b32 v[32:33], v[30:31], v[28:29] op_sel:[1,0]
	v_mov_b32_e32 v31, v29
	v_pk_add_f32 v[28:29], v[32:33], v[30:31]
	s_nop 0
	v_add_f32_e32 v28, v28, v29
	s_nop 1
	v_add_f32_dpp v28, v28, v28 quad_perm:[1,0,3,2] row_mask:0xf bank_mask:0xf
	s_nop 1
	v_add_f32_dpp v28, v28, v28 quad_perm:[2,3,0,1] row_mask:0xf bank_mask:0xf
	s_nop 1
	v_add_f32_dpp v28, v28, v28 row_half_mirror row_mask:0xf bank_mask:0xf
	s_nop 1
	v_add_f32_dpp v28, v28, v28 row_mirror row_mask:0xf bank_mask:0xf
	s_nop 1
	v_add_f32_dpp v28, v28, v28 row_bcast:15 row_mask:0xa bank_mask:0xf
	s_nop 1
	v_add_f32_dpp v28, v28, v28 row_bcast:31 row_mask:0xc bank_mask:0xf
	s_nop 0
	v_readlane_b32 s98, v28, 63
	s_nop 3
	v_mov_b32_e32 v28, s98
	v_fmamk_f32 v28, v28, 0x3b800000, v229
	v_mul_f32_e32 v29, 0x4b800000, v28
	v_cmp_gt_f32_e32 vcc, s3, v28
	s_nop 1
	v_cndmask_b32_e32 v28, v28, v29, vcc
	v_rsq_f32_e32 v28, v28
	s_nop 0
	v_mul_f32_e32 v29, 0x45800000, v28
	v_cndmask_b32_e32 v28, v28, v29, vcc
	v_pk_mul_f32 v[24:25], v[24:25], v[28:29] op_sel_hi:[1,0]
	v_pk_mul_f32 v[26:27], v[26:27], v[28:29] op_sel_hi:[1,0]
	v_pk_fma_f32 v[24:25], v[6:7], v[24:25], v[10:11]
	v_pk_fma_f32 v[26:27], v[8:9], v[26:27], v[12:13]
	v_mul_f32_e32 v28, 0xbfb8aa3b, v24
	v_mul_f32_e32 v29, 0xbfb8aa3b, v25
	v_mul_f32_e32 v30, 0xbfb8aa3b, v26
	v_mul_f32_e32 v31, 0xbfb8aa3b, v27
	v_exp_f32_e32 v28, v28
	v_exp_f32_e32 v29, v29
	v_exp_f32_e32 v30, v30
	v_exp_f32_e32 v31, v31
	v_add_f32_e32 v28, 1.0, v28
	v_add_f32_e32 v29, 1.0, v29
	v_add_f32_e32 v30, 1.0, v30
	v_add_f32_e32 v31, 1.0, v31
	v_rcp_f32_e32 v28, v28
	v_rcp_f32_e32 v29, v29
	v_rcp_f32_e32 v30, v30
	v_rcp_f32_e32 v31, v31
	v_mul_f32_e32 v24, v24, v28
	v_mul_f32_e32 v25, v25, v29
	v_mul_f32_e32 v26, v26, v30
	v_mul_f32_e32 v27, v27, v31
	v_cvt_pk_bf16_f32 v28, v24, v25
	v_cvt_pk_bf16_f32 v29, v26, v27
	ds_read_b128 v[24:27], v23 offset:1024
	global_store_dwordx2 v[14:15], v[28:29], off offset:-2048
	s_waitcnt lgkmcnt(0)
	v_mov_b32_e32 v28, v25
	v_mov_b32_e32 v29, v26
	v_mov_b32_e32 v30, v24
	v_mov_b32_e32 v31, v27
	v_pk_add_f32 v[28:29], v[28:29], v[30:31]
	s_nop 0
	v_add_f32_e32 v23, v28, v29
	s_nop 1
	v_add_f32_dpp v23, v23, v23 quad_perm:[1,0,3,2] row_mask:0xf bank_mask:0xf
	s_nop 1
	v_add_f32_dpp v23, v23, v23 quad_perm:[2,3,0,1] row_mask:0xf bank_mask:0xf
	s_nop 1
	v_add_f32_dpp v23, v23, v23 row_half_mirror row_mask:0xf bank_mask:0xf
	s_nop 1
	v_add_f32_dpp v23, v23, v23 row_mirror row_mask:0xf bank_mask:0xf
	s_nop 1
	v_add_f32_dpp v23, v23, v23 row_bcast:15 row_mask:0xa bank_mask:0xf
	s_nop 1
	v_add_f32_dpp v23, v23, v23 row_bcast:31 row_mask:0xc bank_mask:0xf
	s_nop 0
	v_readlane_b32 s98, v23, 63
	s_nop 3
	v_mov_b32_e32 v23, s98
	v_fmamk_f32 v25, v23, 0xbb800000, v25
	v_fmamk_f32 v24, v23, 0xbb800000, v24
	v_fmamk_f32 v27, v23, 0xbb800000, v27
	v_fmac_f32_e32 v26, 0xbb800000, v23
	v_pk_mul_f32 v[28:29], v[26:27], v[26:27]
	v_pk_mul_f32 v[30:31], v[24:25], v[24:25]
	s_nop 0
	v_pk_mov_b32 v[32:33], v[30:31], v[28:29] op_sel:[1,0]
	v_mov_b32_e32 v31, v29
	v_pk_add_f32 v[28:29], v[32:33], v[30:31]
	s_nop 0
	v_add_f32_e32 v23, v28, v29
	s_nop 1
	v_add_f32_dpp v23, v23, v23 quad_perm:[1,0,3,2] row_mask:0xf bank_mask:0xf
	s_nop 1
	v_add_f32_dpp v23, v23, v23 quad_perm:[2,3,0,1] row_mask:0xf bank_mask:0xf
	s_nop 1
	v_add_f32_dpp v23, v23, v23 row_half_mirror row_mask:0xf bank_mask:0xf
	s_nop 1
	v_add_f32_dpp v23, v23, v23 row_mirror row_mask:0xf bank_mask:0xf
	s_nop 1
	v_add_f32_dpp v23, v23, v23 row_bcast:15 row_mask:0xa bank_mask:0xf
	s_nop 1
	v_add_f32_dpp v23, v23, v23 row_bcast:31 row_mask:0xc bank_mask:0xf
	s_nop 0
	v_readlane_b32 s98, v23, 63
	s_nop 3
	v_mov_b32_e32 v23, s98
	v_fmamk_f32 v23, v23, 0x3b800000, v229
	v_mul_f32_e32 v28, 0x4b800000, v23
	v_cmp_gt_f32_e32 vcc, s3, v23
	s_nop 1
	v_cndmask_b32_e32 v23, v23, v28, vcc
	v_rsq_f32_e32 v23, v23
	s_nop 0
	v_mul_f32_e32 v28, 0x45800000, v23
	v_cndmask_b32_e32 v28, v23, v28, vcc
	v_pk_mul_f32 v[24:25], v[24:25], v[28:29] op_sel_hi:[1,0]
	v_pk_mul_f32 v[26:27], v[26:27], v[28:29] op_sel_hi:[1,0]
	v_pk_fma_f32 v[24:25], v[6:7], v[24:25], v[10:11]
	v_pk_fma_f32 v[26:27], v[8:9], v[26:27], v[12:13]
	v_mul_f32_e32 v23, 0xbfb8aa3b, v24
	v_mul_f32_e32 v28, 0xbfb8aa3b, v25
	v_mul_f32_e32 v29, 0xbfb8aa3b, v26
	v_mul_f32_e32 v30, 0xbfb8aa3b, v27
	v_exp_f32_e32 v23, v23
	v_exp_f32_e32 v28, v28
	v_exp_f32_e32 v29, v29
	v_exp_f32_e32 v30, v30
	v_add_f32_e32 v23, 1.0, v23
	v_add_f32_e32 v28, 1.0, v28
	v_add_f32_e32 v29, 1.0, v29
	v_add_f32_e32 v30, 1.0, v30
	v_rcp_f32_e32 v23, v23
	v_rcp_f32_e32 v28, v28
	v_rcp_f32_e32 v29, v29
	v_rcp_f32_e32 v30, v30
	v_mul_f32_e32 v23, v24, v23
	v_mul_f32_e32 v24, v25, v28
	v_mul_f32_e32 v25, v26, v29
	v_mul_f32_e32 v26, v27, v30
	v_cvt_pk_bf16_f32 v24, v23, v24
	v_cvt_pk_bf16_f32 v25, v25, v26
	global_store_dwordx2 v[14:15], v[24:25], off
	v_lshl_add_u64 v[14:15], v[14:15], 0, s[42:43]
	s_cbranch_scc1 .LBB0_262
	s_waitcnt lgkmcnt(0)
	s_barrier
	s_mov_b64 s[0:1], 0
; __device__ __forceinline__ float fexp(float x) { return __expf(x); }
; __device__ __forceinline__ float frcp(float x) { return __builtin_amdgcn_rcpf(x); }
; __device__ __forceinline__ float sigmoid_f(float x) { return frcp(1.0f + fexp(-x)); }
; __device__ __forceinline__ void hgrn_unit(const Ctx& X, LAS unsigned char* hl, int b, int c, int h, int tid_h, int w4, int lane, int layer) {
;     ...
;     const int i = tid_h >> 2, ds = (tid_h & 3) * 16;
;     const bf16_t* pr = proj + ((size_t)b * T + c * 64 + i) * LDP;
;     float kk[16], qv[16], vv[16];
;     {
;         float ff[16];
;         { float t0[8], t1[8]; unpack8(*(const u32x4*)(pr + C_HF + h * 64 + ds), t0); unpack8(*(const u32x4*)(pr + C_HF + h * 64 + ds + 8), t1);
; #pragma unroll
;           for (int e = 0; e < 8; ++e) { ff[e] = t0[e]; ff[8 + e] = t1[e]; } }
;         { float t0[8], t1[8]; unpack8(*(const u32x4*)(pr + C_HQ + h * 64 + ds), t0); unpack8(*(const u32x4*)(pr + C_HQ + h * 64 + ds + 8), t1);
; #pragma unroll
;           for (int e = 0; e < 8; ++e) { qv[e] = t0[e]; qv[8 + e] = t1[e]; } }
;         { float t0[8], t1[8]; unpack8(*(const u32x4*)(pr + C_HI + h * 64 + ds), t0); unpack8(*(const u32x4*)(pr + C_HI + h * 64 + ds + 8), t1);
; #pragma unroll
;           for (int e = 0; e < 8; ++e) { vv[e] = t0[e]; vv[8 + e] = t1[e]; } }
; #pragma unroll
;         for (int e = 0; e < 16; ++e) {
;             const int ch = h * 64 + ds + e;
;             const float lb = layer == 0 ? 0.f : sigmoid_f(X.in[12][256 + ch] - X.in[12][ch]);
;             const float f = ff[e];
;             const float ls = fminf(f, 0.f) - __logf(1.0f + fexp(-fabsf(f)));
;             const float lf = layer == 0 ? ls : __logf(lb + (1.f - lb) * fexp(ls));
;             kk[e] = (1.f - lb) * frcp(1.f + fexp(f));
;             Gt[i * 64 + ds + e] = lf;
;         }
.LBB0_264:
	s_and_b64 vcc, exec, s[0:1]
	s_cbranch_vccz .LBB0_234
	s_lshl_b32 s0, s6, 1
	s_and_b32 s23, s0, 2
	s_lshr_b32 s22, s6, 8
	s_bfe_u32 s21, s6, 0x70001
	s_add_i32 s23, s23, s33
	s_cmpk_gt_u32 s6, 0x3ff
	s_mov_b64 s[0:1], -1
	s_cbranch_scc0 .LBB0_620
	s_and_b32 s24, s22, 3
	s_and_b32 s0, s6, 0xfffffc00
	s_cmpk_lg_i32 s0, 0x400
	s_mov_b64 s[0:1], -1
	s_cbranch_scc0 .LBB0_318
	v_readlane_b32 s0, v252, 37
	s_lshl_b32 s1, s21, 6
	v_ashrrev_i32_e32 v72, 2, v132
	v_mov_b32_e32 v32, s0
	v_readlane_b32 s0, v252, 38
	v_lshlrev_b32_e32 v36, 4, v132
	v_mov_b64_e32 v[6:7], s[76:77]
	v_mov_b32_e32 v33, s0
	v_readlane_b32 s0, v252, 39
	v_and_b32_e32 v73, 48, v36
	s_lshl_b32 s16, s23, 7
	v_mov_b32_e32 v71, s0
	v_readlane_b32 s0, v252, 40
	v_lshlrev_b32_e32 v156, 1, v73
	v_mov_b32_e32 v74, s36
	s_waitcnt vmcnt(4)
	v_mov_b32_e32 v40, s0
	s_lshl_b32 s0, s24, 13
	s_or_b32 s0, s1, s0
	v_add_u32_e32 v8, s0, v72
	v_mad_i64_i32 v[6:7], s[0:1], v8, s71, v[6:7]
	v_lshl_add_u64 v[6:7], v[6:7], 0, s[16:17]
	v_lshl_add_u64 v[6:7], v[6:7], 0, v[156:157]
	s_mov_b64 s[0:1], 0x1600
	v_lshl_add_u64 v[8:9], v[6:7], 0, s[0:1]
	s_movk_i32 s0, 0x1000
	v_add_co_u32_e32 v10, vcc, s0, v6
	s_mov_b64 s[0:1], 0x1400
	s_nop 0
	v_addc_co_u32_e32 v11, vcc, 0, v7, vcc
	v_add_u32_e32 v70, 0x2400, v71
	v_lshl_add_u64 v[12:13], v[6:7], 0, s[0:1]
	s_mov_b64 s[0:1], 0x1800
	global_load_dwordx4 v[22:25], v[8:9], off offset:16
	global_load_dwordx4 v[18:21], v[10:11], off offset:1024
	v_lshl_add_u64 v[30:31], v[6:7], 0, s[0:1]
	global_load_dwordx4 v[26:29], v[10:11], off offset:1536
	global_load_dwordx4 v[6:9], v[10:11], off offset:2048
	global_load_dwordx4 v[14:17], v[12:13], off offset:16
	s_nop 0
	global_load_dwordx4 v[10:13], v[30:31], off offset:16
	v_readlane_b32 s0, v255, 30
	v_readlane_b32 s1, v255, 31
	v_lshl_or_b32 v30, s23, 6, v73
	v_mov_b32_e32 v41, 0
	v_cndmask_b32_e64 v31, 0, 1, s[0:1]
	v_cmp_ne_u32_e64 s[4:5], 1, v31
	s_andn2_b64 vcc, exec, s[0:1]
	v_mov_b32_e32 v31, 0
	s_cbranch_vccnz .LBB0_269
	v_readlane_b32 s44, v253, 38
	v_mov_b32_e32 v31, v157
	v_readlane_b32 s52, v253, 46
	v_readlane_b32 s53, v253, 47
	s_movk_i32 s44, 0x90
	v_readlane_b32 s45, v253, 39
	v_lshl_add_u64 v[34:35], v[30:31], 2, s[52:53]
	global_load_dwordx4 v[86:89], v[34:35], off
	global_load_dwordx4 v[90:93], v[34:35], off offset:16
	global_load_dwordx4 v[94:97], v[34:35], off offset:32
	global_load_dwordx4 v[98:101], v[34:35], off offset:48
	global_load_dwordx4 v[114:117], v[34:35], off offset:1024
	global_load_dwordx4 v[118:121], v[34:35], off offset:1040
	global_load_dwordx4 v[122:125], v[34:35], off offset:1056
	global_load_dwordx4 v[126:129], v[34:35], off offset:1072
	v_readlane_b32 s46, v253, 40
	v_readlane_b32 s47, v253, 41
	v_readlane_b32 s48, v253, 42
	v_readlane_b32 s49, v253, 43
	v_readlane_b32 s50, v253, 44
	v_readlane_b32 s51, v253, 45
	v_readlane_b32 s54, v253, 48
	v_readlane_b32 s55, v253, 49
	v_readlane_b32 s56, v253, 50
	v_readlane_b32 s57, v253, 51
	v_readlane_b32 s58, v253, 52
	v_readlane_b32 s59, v253, 53
	s_waitcnt vmcnt(0)
	v_sub_f32_e32 v31, v114, v86
	v_mul_f32_e32 v31, 0xbfb8aa3b, v31
	v_exp_f32_e32 v31, v31
	s_nop 0
	v_add_f32_e32 v31, 1.0, v31
	v_rcp_f32_e32 v31, v31
.LBB0_269:
	s_waitcnt vmcnt(3)
	v_lshlrev_b32_e32 v37, 16, v26
	v_mul_f32_e64 v34, |v37|, s66
	v_exp_f32_e32 v34, v34
	s_mov_b32 s0, 0x3f317217
	s_mov_b32 s1, 0x7f800000
	v_add_f32_e32 v34, 1.0, v34
	v_cmp_gt_f32_e32 vcc, s3, v34
	s_nop 1
	v_cndmask_b32_e64 v35, 0, 32, vcc
	v_ldexp_f32 v34, v34, v35
	v_log_f32_e32 v34, v34
	v_cndmask_b32_e32 v38, 0, v231, vcc
	v_max_f32_e32 v35, v37, v37
	v_min_f32_e32 v35, 0, v35
	v_mul_f32_e32 v39, 0x3f317217, v34
	v_fma_f32 v39, v34, s0, -v39
	v_fmac_f32_e32 v39, 0x3377d1cf, v34
	v_fmac_f32_e32 v39, 0x3f317217, v34
	v_cmp_lt_f32_e64 vcc, |v34|, s1
	s_nop 1
	v_cndmask_b32_e32 v34, v34, v39, vcc
	v_sub_f32_e32 v34, v34, v38
	v_sub_f32_e32 v39, v35, v34
	v_mul_f32_e32 v34, 0x3fb8aa3b, v39
	v_exp_f32_e32 v34, v34
	v_sub_f32_e32 v38, 1.0, v31
	v_lshlrev_b32_e32 v35, 8, v72
	v_fmac_f32_e32 v31, v34, v38
	v_cmp_gt_f32_e32 vcc, s3, v31
	s_nop 1
	v_cndmask_b32_e64 v34, 0, 32, vcc
	v_ldexp_f32 v31, v31, v34
	v_log_f32_e32 v31, v31
	v_cndmask_b32_e32 v42, 0, v231, vcc
	v_lshlrev_b32_e32 v34, 2, v73
	v_add3_u32 v35, v32, v35, v34
	v_mul_f32_e32 v43, 0x3f317217, v31
	v_fma_f32 v43, v31, s0, -v43
	v_fmac_f32_e32 v43, 0x3377d1cf, v31
	v_fmac_f32_e32 v43, 0x3f317217, v31
	v_cmp_lt_f32_e64 vcc, |v31|, s1
	s_nop 1
	v_cndmask_b32_e32 v31, v31, v43, vcc
	v_sub_f32_e32 v31, v31, v42
	v_cndmask_b32_e64 v31, v31, v39, s[26:27]
	s_and_b64 vcc, exec, s[4:5]
	ds_write_b32 v35, v31
	s_cbranch_vccnz .LBB0_271
	v_readlane_b32 s44, v253, 38
	v_mov_b32_e32 v31, v157
	v_readlane_b32 s52, v253, 46
	v_readlane_b32 s53, v253, 47
	s_movk_i32 s44, 0x90
	v_readlane_b32 s45, v253, 39
	v_lshl_add_u64 v[42:43], v[30:31], 2, s[52:53]
	v_readlane_b32 s46, v253, 40
	v_readlane_b32 s47, v253, 41
	v_readlane_b32 s48, v253, 42
	v_readlane_b32 s49, v253, 43
	v_readlane_b32 s50, v253, 44
	v_readlane_b32 s51, v253, 45
	v_readlane_b32 s54, v253, 48
	v_readlane_b32 s55, v253, 49
	v_readlane_b32 s56, v253, 50
	v_readlane_b32 s57, v253, 51
	v_readlane_b32 s58, v253, 52
	v_readlane_b32 s59, v253, 53
	s_waitcnt vmcnt(0)
	v_sub_f32_e32 v31, v115, v87
	v_mul_f32_e32 v31, 0xbfb8aa3b, v31
	v_exp_f32_e32 v31, v31
	s_nop 0
	v_add_f32_e32 v31, 1.0, v31
	v_rcp_f32_e32 v41, v31
; __device__ __forceinline__ float fexp(float x) { return __expf(x); }
; __device__ __forceinline__ float frcp(float x) { return __builtin_amdgcn_rcpf(x); }
; __device__ __forceinline__ float sigmoid_f(float x) { return frcp(1.0f + fexp(-x)); }
; __device__ __forceinline__ void hgrn_unit(const Ctx& X, LAS unsigned char* hl, int b, int c, int h, int tid_h, int w4, int lane, int layer) {
;     ...
;         for (int e = 0; e < 16; ++e) {
;             const int ch = h * 64 + ds + e;
;             const float lb = layer == 0 ? 0.f : sigmoid_f(X.in[12][256 + ch] - X.in[12][ch]);
;             const float f = ff[e];
;             const float ls = fminf(f, 0.f) - __logf(1.0f + fexp(-fabsf(f)));
;             const float lf = layer == 0 ? ls : __logf(lb + (1.f - lb) * fexp(ls));
;             kk[e] = (1.f - lb) * frcp(1.f + fexp(f));
;             Gt[i * 64 + ds + e] = lf;
;         }
.LBB0_271:
	v_and_b32_e32 v26, 0xffff0000, v26
	v_mul_f32_e64 v31, |v26|, s66
	v_exp_f32_e32 v31, v31
	s_mov_b32 s6, 0x3f317217
	s_mov_b32 s7, 0x7f800000
	v_mov_b32_e32 v44, 0
	v_add_f32_e32 v31, 1.0, v31
	v_cmp_gt_f32_e32 vcc, s3, v31
	s_nop 1
	v_cndmask_b32_e64 v39, 0, 32, vcc
	v_ldexp_f32 v31, v31, v39
	v_log_f32_e32 v31, v31
	v_cndmask_b32_e32 v42, 0, v231, vcc
	v_max_f32_e32 v39, v26, v26
	v_min_f32_e32 v39, 0, v39
	v_mul_f32_e32 v43, 0x3f317217, v31
	v_fma_f32 v43, v31, s6, -v43
	v_fmac_f32_e32 v43, 0x3377d1cf, v31
	v_fmac_f32_e32 v43, 0x3f317217, v31
	v_cmp_lt_f32_e64 vcc, |v31|, s7
	s_nop 1
	v_cndmask_b32_e32 v31, v31, v43, vcc
	v_sub_f32_e32 v31, v31, v42
	v_sub_f32_e32 v31, v39, v31
	v_mul_f32_e32 v39, 0x3fb8aa3b, v31
	v_exp_f32_e32 v42, v39
	v_sub_f32_e32 v39, 1.0, v41
	s_and_b64 vcc, exec, s[4:5]
	v_fmac_f32_e32 v41, v42, v39
	v_cmp_gt_f32_e64 s[0:1], s3, v41
	s_nop 1
	v_cndmask_b32_e64 v42, 0, 32, s[0:1]
	v_ldexp_f32 v41, v41, v42
	v_log_f32_e32 v41, v41
	v_cndmask_b32_e64 v42, 0, v231, s[0:1]
	v_mul_f32_e32 v43, 0x3f317217, v41
	v_fma_f32 v43, v41, s6, -v43
	v_fmac_f32_e32 v43, 0x3377d1cf, v41
	v_fmac_f32_e32 v43, 0x3f317217, v41
	v_cmp_lt_f32_e64 s[0:1], |v41|, s7
	s_nop 1
	v_cndmask_b32_e64 v41, v41, v43, s[0:1]
	v_sub_f32_e32 v41, v41, v42
	v_cndmask_b32_e64 v31, v41, v31, s[26:27]
	ds_write_b32 v35, v31 offset:4
	v_mov_b32_e32 v31, 0
	s_cbranch_vccnz .LBB0_273
	v_readlane_b32 s44, v253, 38
	v_mov_b32_e32 v31, v157
	v_readlane_b32 s52, v253, 46
	v_readlane_b32 s53, v253, 47
	s_movk_i32 s44, 0x90
	v_readlane_b32 s45, v253, 39
	v_lshl_add_u64 v[42:43], v[30:31], 2, s[52:53]
	v_readlane_b32 s46, v253, 40
	v_readlane_b32 s47, v253, 41
	v_readlane_b32 s48, v253, 42
	v_readlane_b32 s49, v253, 43
	v_readlane_b32 s50, v253, 44
	v_readlane_b32 s51, v253, 45
	v_readlane_b32 s54, v253, 48
	v_readlane_b32 s55, v253, 49
	v_readlane_b32 s56, v253, 50
	v_readlane_b32 s57, v253, 51
	v_readlane_b32 s58, v253, 52
	v_readlane_b32 s59, v253, 53
	s_waitcnt vmcnt(0)
	v_sub_f32_e32 v31, v116, v88
	v_mul_f32_e32 v31, 0xbfb8aa3b, v31
	v_exp_f32_e32 v31, v31
	s_nop 0
	v_add_f32_e32 v31, 1.0, v31
	v_rcp_f32_e32 v31, v31
.LBB0_273:
	v_lshlrev_b32_e32 v41, 16, v27
	v_mul_f32_e64 v42, |v41|, s66
	v_exp_f32_e32 v42, v42
	s_mov_b32 s0, 0x3f317217
	s_mov_b32 s1, 0x7f800000
	v_add_f32_e32 v42, 1.0, v42
	v_cmp_gt_f32_e32 vcc, s3, v42
	s_nop 1
	v_cndmask_b32_e64 v43, 0, 32, vcc
	v_ldexp_f32 v42, v42, v43
	v_log_f32_e32 v42, v42
	v_cndmask_b32_e32 v45, 0, v231, vcc
	v_max_f32_e32 v43, v41, v41
	v_min_f32_e32 v43, 0, v43
	v_mul_f32_e32 v46, 0x3f317217, v42
	v_fma_f32 v46, v42, s0, -v46
	v_fmac_f32_e32 v46, 0x3377d1cf, v42
	v_fmac_f32_e32 v46, 0x3f317217, v42
	v_cmp_lt_f32_e64 vcc, |v42|, s1
	s_nop 1
	v_cndmask_b32_e32 v42, v42, v46, vcc
	v_sub_f32_e32 v42, v42, v45
	v_sub_f32_e32 v43, v43, v42
	v_mul_f32_e32 v42, 0x3fb8aa3b, v43
	v_exp_f32_e32 v45, v42
	v_sub_f32_e32 v42, 1.0, v31
	v_fmac_f32_e32 v31, v45, v42
	v_cmp_gt_f32_e32 vcc, s3, v31
	s_nop 1
	v_cndmask_b32_e64 v45, 0, 32, vcc
	v_ldexp_f32 v31, v31, v45
	v_log_f32_e32 v31, v31
	v_cndmask_b32_e32 v45, 0, v231, vcc
	v_mul_f32_e32 v46, 0x3f317217, v31
	v_fma_f32 v46, v31, s0, -v46
	v_fmac_f32_e32 v46, 0x3377d1cf, v31
	v_fmac_f32_e32 v46, 0x3f317217, v31
	v_cmp_lt_f32_e64 vcc, |v31|, s1
	s_nop 1
	v_cndmask_b32_e32 v31, v31, v46, vcc
	v_sub_f32_e32 v31, v31, v45
	v_cndmask_b32_e64 v31, v31, v43, s[26:27]
	s_and_b64 vcc, exec, s[4:5]
	ds_write_b32 v35, v31 offset:8
	s_cbranch_vccnz .LBB0_275
	v_readlane_b32 s44, v253, 38
	v_mov_b32_e32 v31, v157
	v_readlane_b32 s52, v253, 46
	v_readlane_b32 s53, v253, 47
	s_movk_i32 s44, 0x90
	v_readlane_b32 s45, v253, 39
	v_lshl_add_u64 v[44:45], v[30:31], 2, s[52:53]
	v_readlane_b32 s46, v253, 40
	v_readlane_b32 s47, v253, 41
	v_readlane_b32 s48, v253, 42
	v_readlane_b32 s49, v253, 43
	v_readlane_b32 s50, v253, 44
	v_readlane_b32 s51, v253, 45
	v_readlane_b32 s54, v253, 48
	v_readlane_b32 s55, v253, 49
	v_readlane_b32 s56, v253, 50
	v_readlane_b32 s57, v253, 51
	v_readlane_b32 s58, v253, 52
	v_readlane_b32 s59, v253, 53
	s_waitcnt vmcnt(0)
	v_sub_f32_e32 v31, v117, v89
	v_mul_f32_e32 v31, 0xbfb8aa3b, v31
	v_exp_f32_e32 v31, v31
	s_nop 0
	v_add_f32_e32 v31, 1.0, v31
	v_rcp_f32_e32 v44, v31
.LBB0_275:
	v_and_b32_e32 v27, 0xffff0000, v27
	v_mul_f32_e64 v31, |v27|, s66
	v_exp_f32_e32 v31, v31
	v_mov_b32_e32 v47, 0
	v_add_f32_e32 v31, 1.0, v31
	v_cmp_gt_f32_e32 vcc, s3, v31
	s_nop 1
	v_cndmask_b32_e64 v43, 0, 32, vcc
	v_ldexp_f32 v31, v31, v43
	v_log_f32_e32 v31, v31
	v_cndmask_b32_e32 v45, 0, v231, vcc
	v_max_f32_e32 v43, v27, v27
	v_min_f32_e32 v43, 0, v43
	v_mul_f32_e32 v46, 0x3f317217, v31
	v_fma_f32 v46, v31, s6, -v46
	v_fmac_f32_e32 v46, 0x3377d1cf, v31
	v_fmac_f32_e32 v46, 0x3f317217, v31
	v_cmp_lt_f32_e64 vcc, |v31|, s7
	s_nop 1
	v_cndmask_b32_e32 v31, v31, v46, vcc
	v_sub_f32_e32 v31, v31, v45
	v_sub_f32_e32 v31, v43, v31
	v_mul_f32_e32 v43, 0x3fb8aa3b, v31
	v_exp_f32_e32 v45, v43
	v_sub_f32_e32 v43, 1.0, v44
	s_and_b64 vcc, exec, s[4:5]
	v_fmac_f32_e32 v44, v45, v43
	v_cmp_gt_f32_e64 s[0:1], s3, v44
	s_nop 1
	v_cndmask_b32_e64 v45, 0, 32, s[0:1]
	v_ldexp_f32 v44, v44, v45
	v_log_f32_e32 v44, v44
	v_cndmask_b32_e64 v45, 0, v231, s[0:1]
	v_mul_f32_e32 v46, 0x3f317217, v44
	v_fma_f32 v46, v44, s6, -v46
	v_fmac_f32_e32 v46, 0x3377d1cf, v44
	v_fmac_f32_e32 v46, 0x3f317217, v44
	v_cmp_lt_f32_e64 s[0:1], |v44|, s7
	s_nop 1
	v_cndmask_b32_e64 v44, v44, v46, s[0:1]
	v_sub_f32_e32 v44, v44, v45
	v_cndmask_b32_e64 v31, v44, v31, s[26:27]
	ds_write_b32 v35, v31 offset:12
	v_mov_b32_e32 v31, 0
	s_cbranch_vccnz .LBB0_277
	v_readlane_b32 s44, v253, 38
	v_mov_b32_e32 v31, v157
	v_readlane_b32 s52, v253, 46
	v_readlane_b32 s53, v253, 47
	s_movk_i32 s44, 0x90
	v_readlane_b32 s45, v253, 39
	v_lshl_add_u64 v[44:45], v[30:31], 2, s[52:53]
	v_readlane_b32 s46, v253, 40
	v_readlane_b32 s47, v253, 41
	v_readlane_b32 s48, v253, 42
	v_readlane_b32 s49, v253, 43
	v_readlane_b32 s50, v253, 44
	v_readlane_b32 s51, v253, 45
	v_readlane_b32 s54, v253, 48
	v_readlane_b32 s55, v253, 49
	v_readlane_b32 s56, v253, 50
	v_readlane_b32 s57, v253, 51
	v_readlane_b32 s58, v253, 52
	v_readlane_b32 s59, v253, 53
	s_waitcnt vmcnt(0)
	v_sub_f32_e32 v31, v118, v90
	v_mul_f32_e32 v31, 0xbfb8aa3b, v31
	v_exp_f32_e32 v31, v31
	s_nop 0
	v_add_f32_e32 v31, 1.0, v31
	v_rcp_f32_e32 v31, v31
; __device__ __forceinline__ float fexp(float x) { return __expf(x); }
; __device__ __forceinline__ float frcp(float x) { return __builtin_amdgcn_rcpf(x); }
; __device__ __forceinline__ float sigmoid_f(float x) { return frcp(1.0f + fexp(-x)); }
; __device__ __forceinline__ void hgrn_unit(const Ctx& X, LAS unsigned char* hl, int b, int c, int h, int tid_h, int w4, int lane, int layer) {
;     ...
;         for (int e = 0; e < 16; ++e) {
;             const int ch = h * 64 + ds + e;
;             const float lb = layer == 0 ? 0.f : sigmoid_f(X.in[12][256 + ch] - X.in[12][ch]);
;             const float f = ff[e];
;             const float ls = fminf(f, 0.f) - __logf(1.0f + fexp(-fabsf(f)));
;             const float lf = layer == 0 ? ls : __logf(lb + (1.f - lb) * fexp(ls));
;             kk[e] = (1.f - lb) * frcp(1.f + fexp(f));
;             Gt[i * 64 + ds + e] = lf;
;         }
.LBB0_277:
	v_lshlrev_b32_e32 v44, 16, v28
	v_mul_f32_e64 v45, |v44|, s66
	v_exp_f32_e32 v45, v45
	s_mov_b32 s0, 0x3f317217
	s_mov_b32 s1, 0x7f800000
	v_add_f32_e32 v45, 1.0, v45
	v_cmp_gt_f32_e32 vcc, s3, v45
	s_nop 1
	v_cndmask_b32_e64 v46, 0, 32, vcc
	v_ldexp_f32 v45, v45, v46
	v_log_f32_e32 v45, v45
	v_cndmask_b32_e32 v48, 0, v231, vcc
	v_max_f32_e32 v46, v44, v44
	v_min_f32_e32 v46, 0, v46
	v_mul_f32_e32 v49, 0x3f317217, v45
	v_fma_f32 v49, v45, s0, -v49
	v_fmac_f32_e32 v49, 0x3377d1cf, v45
	v_fmac_f32_e32 v49, 0x3f317217, v45
	v_cmp_lt_f32_e64 vcc, |v45|, s1
	s_nop 1
	v_cndmask_b32_e32 v45, v45, v49, vcc
	v_sub_f32_e32 v45, v45, v48
	v_sub_f32_e32 v46, v46, v45
	v_mul_f32_e32 v45, 0x3fb8aa3b, v46
	v_exp_f32_e32 v48, v45
	v_sub_f32_e32 v45, 1.0, v31
	v_fmac_f32_e32 v31, v48, v45
	v_cmp_gt_f32_e32 vcc, s3, v31
	s_nop 1
	v_cndmask_b32_e64 v48, 0, 32, vcc
	v_ldexp_f32 v31, v31, v48
	v_log_f32_e32 v31, v31
	v_cndmask_b32_e32 v48, 0, v231, vcc
	v_mul_f32_e32 v49, 0x3f317217, v31
	v_fma_f32 v49, v31, s0, -v49
	v_fmac_f32_e32 v49, 0x3377d1cf, v31
	v_fmac_f32_e32 v49, 0x3f317217, v31
	v_cmp_lt_f32_e64 vcc, |v31|, s1
	s_nop 1
	v_cndmask_b32_e32 v31, v31, v49, vcc
	v_sub_f32_e32 v31, v31, v48
	v_cndmask_b32_e64 v31, v31, v46, s[26:27]
	s_and_b64 vcc, exec, s[4:5]
	ds_write_b32 v35, v31 offset:16
	s_cbranch_vccnz .LBB0_279
	v_readlane_b32 s44, v253, 38
	v_mov_b32_e32 v31, v157
	v_readlane_b32 s52, v253, 46
	v_readlane_b32 s53, v253, 47
	s_movk_i32 s44, 0x90
	v_readlane_b32 s45, v253, 39
	v_lshl_add_u64 v[46:47], v[30:31], 2, s[52:53]
	v_readlane_b32 s46, v253, 40
	v_readlane_b32 s47, v253, 41
	v_readlane_b32 s48, v253, 42
	v_readlane_b32 s49, v253, 43
	v_readlane_b32 s50, v253, 44
	v_readlane_b32 s51, v253, 45
	v_readlane_b32 s54, v253, 48
	v_readlane_b32 s55, v253, 49
	v_readlane_b32 s56, v253, 50
	v_readlane_b32 s57, v253, 51
	v_readlane_b32 s58, v253, 52
	v_readlane_b32 s59, v253, 53
	s_waitcnt vmcnt(0)
	v_sub_f32_e32 v31, v119, v91
	v_mul_f32_e32 v31, 0xbfb8aa3b, v31
	v_exp_f32_e32 v31, v31
	s_nop 0
	v_add_f32_e32 v31, 1.0, v31
	v_rcp_f32_e32 v47, v31
.LBB0_279:
	v_and_b32_e32 v28, 0xffff0000, v28
	v_mul_f32_e64 v31, |v28|, s66
	v_exp_f32_e32 v31, v31
	v_mov_b32_e32 v50, 0
	v_add_f32_e32 v31, 1.0, v31
	v_cmp_gt_f32_e32 vcc, s3, v31
	s_nop 1
	v_cndmask_b32_e64 v46, 0, 32, vcc
	v_ldexp_f32 v31, v31, v46
	v_log_f32_e32 v31, v31
	v_cndmask_b32_e32 v48, 0, v231, vcc
	v_max_f32_e32 v46, v28, v28
	v_min_f32_e32 v46, 0, v46
	v_mul_f32_e32 v49, 0x3f317217, v31
	v_fma_f32 v49, v31, s6, -v49
	v_fmac_f32_e32 v49, 0x3377d1cf, v31
	v_fmac_f32_e32 v49, 0x3f317217, v31
	v_cmp_lt_f32_e64 vcc, |v31|, s7
	s_nop 1
	v_cndmask_b32_e32 v31, v31, v49, vcc
	v_sub_f32_e32 v31, v31, v48
	v_sub_f32_e32 v31, v46, v31
	v_mul_f32_e32 v46, 0x3fb8aa3b, v31
	v_exp_f32_e32 v48, v46
	v_sub_f32_e32 v46, 1.0, v47
	s_and_b64 vcc, exec, s[4:5]
	v_fmac_f32_e32 v47, v48, v46
	v_cmp_gt_f32_e64 s[0:1], s3, v47
	s_nop 1
	v_cndmask_b32_e64 v48, 0, 32, s[0:1]
	v_ldexp_f32 v47, v47, v48
	v_log_f32_e32 v47, v47
	v_cndmask_b32_e64 v48, 0, v231, s[0:1]
	v_mul_f32_e32 v49, 0x3f317217, v47
	v_fma_f32 v49, v47, s6, -v49
	v_fmac_f32_e32 v49, 0x3377d1cf, v47
	v_fmac_f32_e32 v49, 0x3f317217, v47
	v_cmp_lt_f32_e64 s[0:1], |v47|, s7
	s_nop 1
	v_cndmask_b32_e64 v47, v47, v49, s[0:1]
	v_sub_f32_e32 v47, v47, v48
	v_cndmask_b32_e64 v31, v47, v31, s[26:27]
	ds_write_b32 v35, v31 offset:20
	v_mov_b32_e32 v31, 0
	s_cbranch_vccnz .LBB0_281
	v_readlane_b32 s44, v253, 38
	v_mov_b32_e32 v31, v157
	v_readlane_b32 s52, v253, 46
	v_readlane_b32 s53, v253, 47
	s_movk_i32 s44, 0x90
	v_readlane_b32 s45, v253, 39
	v_lshl_add_u64 v[48:49], v[30:31], 2, s[52:53]
	v_readlane_b32 s46, v253, 40
	v_readlane_b32 s47, v253, 41
	v_readlane_b32 s48, v253, 42
	v_readlane_b32 s49, v253, 43
	v_readlane_b32 s50, v253, 44
	v_readlane_b32 s51, v253, 45
	v_readlane_b32 s54, v253, 48
	v_readlane_b32 s55, v253, 49
	v_readlane_b32 s56, v253, 50
	v_readlane_b32 s57, v253, 51
	v_readlane_b32 s58, v253, 52
	v_readlane_b32 s59, v253, 53
	s_waitcnt vmcnt(0)
	v_sub_f32_e32 v31, v120, v92
	v_mul_f32_e32 v31, 0xbfb8aa3b, v31
	v_exp_f32_e32 v31, v31
	s_nop 0
	v_add_f32_e32 v31, 1.0, v31
	v_rcp_f32_e32 v31, v31
.LBB0_281:
	v_lshlrev_b32_e32 v47, 16, v29
	v_mul_f32_e64 v48, |v47|, s66
	v_exp_f32_e32 v48, v48
	s_mov_b32 s0, 0x3f317217
	s_mov_b32 s1, 0x7f800000
	v_add_f32_e32 v48, 1.0, v48
	v_cmp_gt_f32_e32 vcc, s3, v48
	s_nop 1
	v_cndmask_b32_e64 v49, 0, 32, vcc
	v_ldexp_f32 v48, v48, v49
	v_log_f32_e32 v48, v48
	v_cndmask_b32_e32 v51, 0, v231, vcc
	v_max_f32_e32 v49, v47, v47
	v_min_f32_e32 v49, 0, v49
	v_mul_f32_e32 v52, 0x3f317217, v48
	v_fma_f32 v52, v48, s0, -v52
	v_fmac_f32_e32 v52, 0x3377d1cf, v48
	v_fmac_f32_e32 v52, 0x3f317217, v48
	v_cmp_lt_f32_e64 vcc, |v48|, s1
	s_nop 1
	v_cndmask_b32_e32 v48, v48, v52, vcc
	v_sub_f32_e32 v48, v48, v51
	v_sub_f32_e32 v49, v49, v48
	v_mul_f32_e32 v48, 0x3fb8aa3b, v49
	v_exp_f32_e32 v51, v48
	v_sub_f32_e32 v48, 1.0, v31
	v_fmac_f32_e32 v31, v51, v48
	v_cmp_gt_f32_e32 vcc, s3, v31
	s_nop 1
	v_cndmask_b32_e64 v51, 0, 32, vcc
	v_ldexp_f32 v31, v31, v51
	v_log_f32_e32 v31, v31
	v_cndmask_b32_e32 v51, 0, v231, vcc
	v_mul_f32_e32 v52, 0x3f317217, v31
	v_fma_f32 v52, v31, s0, -v52
	v_fmac_f32_e32 v52, 0x3377d1cf, v31
	v_fmac_f32_e32 v52, 0x3f317217, v31
	v_cmp_lt_f32_e64 vcc, |v31|, s1
	s_nop 1
	v_cndmask_b32_e32 v31, v31, v52, vcc
	v_sub_f32_e32 v31, v31, v51
	v_cndmask_b32_e64 v31, v31, v49, s[26:27]
	s_and_b64 vcc, exec, s[4:5]
	ds_write_b32 v35, v31 offset:24
	s_cbranch_vccnz .LBB0_283
	v_readlane_b32 s44, v253, 38
	v_mov_b32_e32 v31, v157
	v_readlane_b32 s52, v253, 46
	v_readlane_b32 s53, v253, 47
	s_movk_i32 s44, 0x90
	v_readlane_b32 s45, v253, 39
	v_lshl_add_u64 v[50:51], v[30:31], 2, s[52:53]
	v_readlane_b32 s46, v253, 40
	v_readlane_b32 s47, v253, 41
	v_readlane_b32 s48, v253, 42
	v_readlane_b32 s49, v253, 43
	v_readlane_b32 s50, v253, 44
	v_readlane_b32 s51, v253, 45
	v_readlane_b32 s54, v253, 48
	v_readlane_b32 s55, v253, 49
	v_readlane_b32 s56, v253, 50
	v_readlane_b32 s57, v253, 51
	v_readlane_b32 s58, v253, 52
	v_readlane_b32 s59, v253, 53
	s_waitcnt vmcnt(0)
	v_sub_f32_e32 v31, v121, v93
	v_mul_f32_e32 v31, 0xbfb8aa3b, v31
	v_exp_f32_e32 v31, v31
	s_nop 0
	v_add_f32_e32 v31, 1.0, v31
	v_rcp_f32_e32 v50, v31
; __device__ __forceinline__ float fexp(float x) { return __expf(x); }
; __device__ __forceinline__ float frcp(float x) { return __builtin_amdgcn_rcpf(x); }
; __device__ __forceinline__ float sigmoid_f(float x) { return frcp(1.0f + fexp(-x)); }
; __device__ __forceinline__ void hgrn_unit(const Ctx& X, LAS unsigned char* hl, int b, int c, int h, int tid_h, int w4, int lane, int layer) {
;     ...
;         for (int e = 0; e < 16; ++e) {
;             const int ch = h * 64 + ds + e;
;             const float lb = layer == 0 ? 0.f : sigmoid_f(X.in[12][256 + ch] - X.in[12][ch]);
;             const float f = ff[e];
;             const float ls = fminf(f, 0.f) - __logf(1.0f + fexp(-fabsf(f)));
;             const float lf = layer == 0 ? ls : __logf(lb + (1.f - lb) * fexp(ls));
;             kk[e] = (1.f - lb) * frcp(1.f + fexp(f));
;             Gt[i * 64 + ds + e] = lf;
;         }
.LBB0_283:
	v_and_b32_e32 v29, 0xffff0000, v29
	v_mul_f32_e64 v31, |v29|, s66
	v_exp_f32_e32 v31, v31
	v_mov_b32_e32 v53, 0
	v_add_f32_e32 v31, 1.0, v31
	v_cmp_gt_f32_e32 vcc, s3, v31
	s_nop 1
	v_cndmask_b32_e64 v49, 0, 32, vcc
	v_ldexp_f32 v31, v31, v49
	v_log_f32_e32 v31, v31
	v_cndmask_b32_e32 v51, 0, v231, vcc
	v_max_f32_e32 v49, v29, v29
	v_min_f32_e32 v49, 0, v49
	v_mul_f32_e32 v52, 0x3f317217, v31
	v_fma_f32 v52, v31, s6, -v52
	v_fmac_f32_e32 v52, 0x3377d1cf, v31
	v_fmac_f32_e32 v52, 0x3f317217, v31
	v_cmp_lt_f32_e64 vcc, |v31|, s7
	s_nop 1
	v_cndmask_b32_e32 v31, v31, v52, vcc
	v_sub_f32_e32 v31, v31, v51
	v_sub_f32_e32 v31, v49, v31
	v_mul_f32_e32 v49, 0x3fb8aa3b, v31
	v_exp_f32_e32 v51, v49
	v_sub_f32_e32 v49, 1.0, v50
	s_and_b64 vcc, exec, s[4:5]
	v_fmac_f32_e32 v50, v51, v49
	v_cmp_gt_f32_e64 s[0:1], s3, v50
	s_nop 1
	v_cndmask_b32_e64 v51, 0, 32, s[0:1]
	v_ldexp_f32 v50, v50, v51
	v_log_f32_e32 v50, v50
	v_cndmask_b32_e64 v51, 0, v231, s[0:1]
	v_mul_f32_e32 v52, 0x3f317217, v50
	v_fma_f32 v52, v50, s6, -v52
	v_fmac_f32_e32 v52, 0x3377d1cf, v50
	v_fmac_f32_e32 v52, 0x3f317217, v50
	v_cmp_lt_f32_e64 s[0:1], |v50|, s7
	s_nop 1
	v_cndmask_b32_e64 v50, v50, v52, s[0:1]
	v_sub_f32_e32 v50, v50, v51
	v_cndmask_b32_e64 v31, v50, v31, s[26:27]
	ds_write_b32 v35, v31 offset:28
	v_mov_b32_e32 v31, 0
	s_cbranch_vccnz .LBB0_285
	v_readlane_b32 s44, v253, 38
	v_mov_b32_e32 v31, v157
	v_readlane_b32 s52, v253, 46
	v_readlane_b32 s53, v253, 47
	s_movk_i32 s44, 0x90
	v_readlane_b32 s45, v253, 39
	v_lshl_add_u64 v[50:51], v[30:31], 2, s[52:53]
	v_readlane_b32 s46, v253, 40
	v_readlane_b32 s47, v253, 41
	v_readlane_b32 s48, v253, 42
	v_readlane_b32 s49, v253, 43
	v_readlane_b32 s50, v253, 44
	v_readlane_b32 s51, v253, 45
	v_readlane_b32 s54, v253, 48
	v_readlane_b32 s55, v253, 49
	v_readlane_b32 s56, v253, 50
	v_readlane_b32 s57, v253, 51
	v_readlane_b32 s58, v253, 52
	v_readlane_b32 s59, v253, 53
	s_waitcnt vmcnt(0)
	v_sub_f32_e32 v31, v122, v94
	v_mul_f32_e32 v31, 0xbfb8aa3b, v31
	v_exp_f32_e32 v31, v31
	s_nop 0
	v_add_f32_e32 v31, 1.0, v31
	v_rcp_f32_e32 v31, v31
.LBB0_285:
	v_lshlrev_b32_e32 v50, 16, v22
	v_mul_f32_e64 v51, |v50|, s66
	v_exp_f32_e32 v51, v51
	s_mov_b32 s0, 0x3f317217
	s_mov_b32 s1, 0x7f800000
	v_add_f32_e32 v51, 1.0, v51
	v_cmp_gt_f32_e32 vcc, s3, v51
	s_nop 1
	v_cndmask_b32_e64 v52, 0, 32, vcc
	v_ldexp_f32 v51, v51, v52
	v_log_f32_e32 v51, v51
	v_cndmask_b32_e32 v54, 0, v231, vcc
	v_max_f32_e32 v52, v50, v50
	v_min_f32_e32 v52, 0, v52
	v_mul_f32_e32 v55, 0x3f317217, v51
	v_fma_f32 v55, v51, s0, -v55
	v_fmac_f32_e32 v55, 0x3377d1cf, v51
	v_fmac_f32_e32 v55, 0x3f317217, v51
	v_cmp_lt_f32_e64 vcc, |v51|, s1
	s_nop 1
	v_cndmask_b32_e32 v51, v51, v55, vcc
	v_sub_f32_e32 v51, v51, v54
	v_sub_f32_e32 v52, v52, v51
	v_mul_f32_e32 v51, 0x3fb8aa3b, v52
	v_exp_f32_e32 v54, v51
	v_sub_f32_e32 v51, 1.0, v31
	v_fmac_f32_e32 v31, v54, v51
	v_cmp_gt_f32_e32 vcc, s3, v31
	s_nop 1
	v_cndmask_b32_e64 v54, 0, 32, vcc
	v_ldexp_f32 v31, v31, v54
	v_log_f32_e32 v31, v31
	v_cndmask_b32_e32 v54, 0, v231, vcc
	v_mul_f32_e32 v55, 0x3f317217, v31
	v_fma_f32 v55, v31, s0, -v55
	v_fmac_f32_e32 v55, 0x3377d1cf, v31
	v_fmac_f32_e32 v55, 0x3f317217, v31
	v_cmp_lt_f32_e64 vcc, |v31|, s1
	s_nop 1
	v_cndmask_b32_e32 v31, v31, v55, vcc
	v_sub_f32_e32 v31, v31, v54
	v_cndmask_b32_e64 v31, v31, v52, s[26:27]
	s_and_b64 vcc, exec, s[4:5]
	ds_write_b32 v35, v31 offset:32
	s_cbranch_vccnz .LBB0_287
	v_readlane_b32 s44, v253, 38
	v_mov_b32_e32 v31, v157
	v_readlane_b32 s52, v253, 46
	v_readlane_b32 s53, v253, 47
	s_movk_i32 s44, 0x90
	v_readlane_b32 s45, v253, 39
	v_lshl_add_u64 v[52:53], v[30:31], 2, s[52:53]
	v_readlane_b32 s46, v253, 40
	v_readlane_b32 s47, v253, 41
	v_readlane_b32 s48, v253, 42
	v_readlane_b32 s49, v253, 43
	v_readlane_b32 s50, v253, 44
	v_readlane_b32 s51, v253, 45
	v_readlane_b32 s54, v253, 48
	v_readlane_b32 s55, v253, 49
	v_readlane_b32 s56, v253, 50
	v_readlane_b32 s57, v253, 51
	v_readlane_b32 s58, v253, 52
	v_readlane_b32 s59, v253, 53
	s_waitcnt vmcnt(0)
	v_sub_f32_e32 v31, v123, v95
	v_mul_f32_e32 v31, 0xbfb8aa3b, v31
	v_exp_f32_e32 v31, v31
	s_nop 0
	v_add_f32_e32 v31, 1.0, v31
	v_rcp_f32_e32 v53, v31
.LBB0_287:
	v_and_b32_e32 v22, 0xffff0000, v22
	v_mul_f32_e64 v31, |v22|, s66
	v_exp_f32_e32 v31, v31
	v_mov_b32_e32 v56, 0
	v_add_f32_e32 v31, 1.0, v31
	v_cmp_gt_f32_e32 vcc, s3, v31
	s_nop 1
	v_cndmask_b32_e64 v52, 0, 32, vcc
	v_ldexp_f32 v31, v31, v52
	v_log_f32_e32 v31, v31
	v_cndmask_b32_e32 v54, 0, v231, vcc
	v_max_f32_e32 v52, v22, v22
	v_min_f32_e32 v52, 0, v52
	v_mul_f32_e32 v55, 0x3f317217, v31
	v_fma_f32 v55, v31, s6, -v55
	v_fmac_f32_e32 v55, 0x3377d1cf, v31
	v_fmac_f32_e32 v55, 0x3f317217, v31
	v_cmp_lt_f32_e64 vcc, |v31|, s7
	s_nop 1
	v_cndmask_b32_e32 v31, v31, v55, vcc
	v_sub_f32_e32 v31, v31, v54
	v_sub_f32_e32 v31, v52, v31
	v_mul_f32_e32 v52, 0x3fb8aa3b, v31
	v_exp_f32_e32 v54, v52
	v_sub_f32_e32 v52, 1.0, v53
	s_and_b64 vcc, exec, s[4:5]
	v_fmac_f32_e32 v53, v54, v52
	v_cmp_gt_f32_e64 s[0:1], s3, v53
	s_nop 1
	v_cndmask_b32_e64 v54, 0, 32, s[0:1]
	v_ldexp_f32 v53, v53, v54
	v_log_f32_e32 v53, v53
	v_cndmask_b32_e64 v54, 0, v231, s[0:1]
	v_mul_f32_e32 v55, 0x3f317217, v53
	v_fma_f32 v55, v53, s6, -v55
	v_fmac_f32_e32 v55, 0x3377d1cf, v53
	v_fmac_f32_e32 v55, 0x3f317217, v53
	v_cmp_lt_f32_e64 s[0:1], |v53|, s7
	s_nop 1
	v_cndmask_b32_e64 v53, v53, v55, s[0:1]
	v_sub_f32_e32 v53, v53, v54
	v_cndmask_b32_e64 v31, v53, v31, s[26:27]
	ds_write_b32 v35, v31 offset:36
	v_mov_b32_e32 v31, 0
	s_cbranch_vccnz .LBB0_289
	v_readlane_b32 s44, v253, 38
	v_mov_b32_e32 v31, v157
	v_readlane_b32 s52, v253, 46
	v_readlane_b32 s53, v253, 47
	s_movk_i32 s44, 0x90
	v_readlane_b32 s45, v253, 39
	v_lshl_add_u64 v[54:55], v[30:31], 2, s[52:53]
	v_readlane_b32 s46, v253, 40
	v_readlane_b32 s47, v253, 41
	v_readlane_b32 s48, v253, 42
	v_readlane_b32 s49, v253, 43
	v_readlane_b32 s50, v253, 44
	v_readlane_b32 s51, v253, 45
	v_readlane_b32 s54, v253, 48
	v_readlane_b32 s55, v253, 49
	v_readlane_b32 s56, v253, 50
	v_readlane_b32 s57, v253, 51
	v_readlane_b32 s58, v253, 52
	v_readlane_b32 s59, v253, 53
	s_waitcnt vmcnt(0)
	v_sub_f32_e32 v31, v124, v96
	v_mul_f32_e32 v31, 0xbfb8aa3b, v31
	v_exp_f32_e32 v31, v31
	s_nop 0
	v_add_f32_e32 v31, 1.0, v31
	v_rcp_f32_e32 v31, v31
; __device__ __forceinline__ float fexp(float x) { return __expf(x); }
; __device__ __forceinline__ float frcp(float x) { return __builtin_amdgcn_rcpf(x); }
; __device__ __forceinline__ float sigmoid_f(float x) { return frcp(1.0f + fexp(-x)); }
; __device__ __forceinline__ void hgrn_unit(const Ctx& X, LAS unsigned char* hl, int b, int c, int h, int tid_h, int w4, int lane, int layer) {
;     ...
;         for (int e = 0; e < 16; ++e) {
;             const int ch = h * 64 + ds + e;
;             const float lb = layer == 0 ? 0.f : sigmoid_f(X.in[12][256 + ch] - X.in[12][ch]);
;             const float f = ff[e];
;             const float ls = fminf(f, 0.f) - __logf(1.0f + fexp(-fabsf(f)));
;             const float lf = layer == 0 ? ls : __logf(lb + (1.f - lb) * fexp(ls));
;             kk[e] = (1.f - lb) * frcp(1.f + fexp(f));
;             Gt[i * 64 + ds + e] = lf;
;         }
.LBB0_289:
	v_lshlrev_b32_e32 v53, 16, v23
	v_mul_f32_e64 v54, |v53|, s66
	v_exp_f32_e32 v54, v54
	s_mov_b32 s0, 0x3f317217
	s_mov_b32 s1, 0x7f800000
	v_add_f32_e32 v54, 1.0, v54
	v_cmp_gt_f32_e32 vcc, s3, v54
	s_nop 1
	v_cndmask_b32_e64 v55, 0, 32, vcc
	v_ldexp_f32 v54, v54, v55
	v_log_f32_e32 v54, v54
	v_cndmask_b32_e32 v57, 0, v231, vcc
	v_max_f32_e32 v55, v53, v53
	v_min_f32_e32 v55, 0, v55
	v_mul_f32_e32 v58, 0x3f317217, v54
	v_fma_f32 v58, v54, s0, -v58
	v_fmac_f32_e32 v58, 0x3377d1cf, v54
	v_fmac_f32_e32 v58, 0x3f317217, v54
	v_cmp_lt_f32_e64 vcc, |v54|, s1
	s_nop 1
	v_cndmask_b32_e32 v54, v54, v58, vcc
	v_sub_f32_e32 v54, v54, v57
	v_sub_f32_e32 v55, v55, v54
	v_mul_f32_e32 v54, 0x3fb8aa3b, v55
	v_exp_f32_e32 v57, v54
	v_sub_f32_e32 v54, 1.0, v31
	v_fmac_f32_e32 v31, v57, v54
	v_cmp_gt_f32_e32 vcc, s3, v31
	s_nop 1
	v_cndmask_b32_e64 v57, 0, 32, vcc
	v_ldexp_f32 v31, v31, v57
	v_log_f32_e32 v31, v31
	v_cndmask_b32_e32 v57, 0, v231, vcc
	v_mul_f32_e32 v58, 0x3f317217, v31
	v_fma_f32 v58, v31, s0, -v58
	v_fmac_f32_e32 v58, 0x3377d1cf, v31
	v_fmac_f32_e32 v58, 0x3f317217, v31
	v_cmp_lt_f32_e64 vcc, |v31|, s1
	s_nop 1
	v_cndmask_b32_e32 v31, v31, v58, vcc
	v_sub_f32_e32 v31, v31, v57
	v_cndmask_b32_e64 v31, v31, v55, s[26:27]
	s_and_b64 vcc, exec, s[4:5]
	ds_write_b32 v35, v31 offset:40
	s_cbranch_vccnz .LBB0_291
	v_readlane_b32 s44, v253, 38
	v_mov_b32_e32 v31, v157
	v_readlane_b32 s52, v253, 46
	v_readlane_b32 s53, v253, 47
	s_movk_i32 s44, 0x90
	v_readlane_b32 s45, v253, 39
	v_lshl_add_u64 v[56:57], v[30:31], 2, s[52:53]
	v_readlane_b32 s46, v253, 40
	v_readlane_b32 s47, v253, 41
	v_readlane_b32 s48, v253, 42
	v_readlane_b32 s49, v253, 43
	v_readlane_b32 s50, v253, 44
	v_readlane_b32 s51, v253, 45
	v_readlane_b32 s54, v253, 48
	v_readlane_b32 s55, v253, 49
	v_readlane_b32 s56, v253, 50
	v_readlane_b32 s57, v253, 51
	v_readlane_b32 s58, v253, 52
	v_readlane_b32 s59, v253, 53
	s_waitcnt vmcnt(0)
	v_sub_f32_e32 v31, v125, v97
	v_mul_f32_e32 v31, 0xbfb8aa3b, v31
	v_exp_f32_e32 v31, v31
	s_nop 0
	v_add_f32_e32 v31, 1.0, v31
	v_rcp_f32_e32 v56, v31
.LBB0_291:
	v_and_b32_e32 v23, 0xffff0000, v23
	v_mul_f32_e64 v31, |v23|, s66
	v_exp_f32_e32 v31, v31
	v_mov_b32_e32 v60, 0
	v_add_f32_e32 v31, 1.0, v31
	v_cmp_gt_f32_e32 vcc, s3, v31
	s_nop 1
	v_cndmask_b32_e64 v55, 0, 32, vcc
	v_ldexp_f32 v31, v31, v55
	v_log_f32_e32 v31, v31
	v_cndmask_b32_e32 v57, 0, v231, vcc
	v_max_f32_e32 v55, v23, v23
	v_min_f32_e32 v55, 0, v55
	v_mul_f32_e32 v58, 0x3f317217, v31
	v_fma_f32 v58, v31, s6, -v58
	v_fmac_f32_e32 v58, 0x3377d1cf, v31
	v_fmac_f32_e32 v58, 0x3f317217, v31
	v_cmp_lt_f32_e64 vcc, |v31|, s7
	s_nop 1
	v_cndmask_b32_e32 v31, v31, v58, vcc
	v_sub_f32_e32 v31, v31, v57
	v_sub_f32_e32 v31, v55, v31
	v_mul_f32_e32 v55, 0x3fb8aa3b, v31
	v_exp_f32_e32 v57, v55
	v_sub_f32_e32 v55, 1.0, v56
	s_and_b64 vcc, exec, s[4:5]
	v_fmac_f32_e32 v56, v57, v55
	v_cmp_gt_f32_e64 s[0:1], s3, v56
	s_nop 1
	v_cndmask_b32_e64 v57, 0, 32, s[0:1]
	v_ldexp_f32 v56, v56, v57
	v_log_f32_e32 v56, v56
	v_cndmask_b32_e64 v57, 0, v231, s[0:1]
	v_mul_f32_e32 v58, 0x3f317217, v56
	v_fma_f32 v58, v56, s6, -v58
	v_fmac_f32_e32 v58, 0x3377d1cf, v56
	v_fmac_f32_e32 v58, 0x3f317217, v56
	v_cmp_lt_f32_e64 s[0:1], |v56|, s7
	s_nop 1
	v_cndmask_b32_e64 v56, v56, v58, s[0:1]
	v_sub_f32_e32 v56, v56, v57
	v_cndmask_b32_e64 v31, v56, v31, s[26:27]
	ds_write_b32 v35, v31 offset:44
	v_mov_b32_e32 v31, 0
	s_cbranch_vccnz .LBB0_293
	v_readlane_b32 s44, v253, 38
	v_mov_b32_e32 v31, v157
	v_readlane_b32 s52, v253, 46
	v_readlane_b32 s53, v253, 47
	s_movk_i32 s44, 0x90
	v_readlane_b32 s45, v253, 39
	v_lshl_add_u64 v[56:57], v[30:31], 2, s[52:53]
	v_readlane_b32 s46, v253, 40
	v_readlane_b32 s47, v253, 41
	v_readlane_b32 s48, v253, 42
	v_readlane_b32 s49, v253, 43
	v_readlane_b32 s50, v253, 44
	v_readlane_b32 s51, v253, 45
	v_readlane_b32 s54, v253, 48
	v_readlane_b32 s55, v253, 49
	v_readlane_b32 s56, v253, 50
	v_readlane_b32 s57, v253, 51
	v_readlane_b32 s58, v253, 52
	v_readlane_b32 s59, v253, 53
	s_waitcnt vmcnt(0)
	v_sub_f32_e32 v31, v126, v98
	v_mul_f32_e32 v31, 0xbfb8aa3b, v31
	v_exp_f32_e32 v31, v31
	s_nop 0
	v_add_f32_e32 v31, 1.0, v31
	v_rcp_f32_e32 v31, v31
.LBB0_293:
	v_lshlrev_b32_e32 v56, 16, v24
	v_mul_f32_e64 v57, |v56|, s66
	v_exp_f32_e32 v57, v57
	s_mov_b32 s0, 0x3f317217
	s_mov_b32 s1, 0x7f800000
	v_add_f32_e32 v57, 1.0, v57
	v_cmp_gt_f32_e32 vcc, s3, v57
	s_nop 1
	v_cndmask_b32_e64 v58, 0, 32, vcc
	v_ldexp_f32 v57, v57, v58
	v_log_f32_e32 v57, v57
	v_cndmask_b32_e32 v59, 0, v231, vcc
	v_max_f32_e32 v58, v56, v56
	v_min_f32_e32 v58, 0, v58
	v_mul_f32_e32 v61, 0x3f317217, v57
	v_fma_f32 v61, v57, s0, -v61
	v_fmac_f32_e32 v61, 0x3377d1cf, v57
	v_fmac_f32_e32 v61, 0x3f317217, v57
	v_cmp_lt_f32_e64 vcc, |v57|, s1
	s_nop 1
	v_cndmask_b32_e32 v57, v57, v61, vcc
	v_sub_f32_e32 v57, v57, v59
	v_sub_f32_e32 v58, v58, v57
	v_mul_f32_e32 v57, 0x3fb8aa3b, v58
	v_exp_f32_e32 v59, v57
	v_sub_f32_e32 v57, 1.0, v31
	v_fmac_f32_e32 v31, v59, v57
	v_cmp_gt_f32_e32 vcc, s3, v31
	s_nop 1
	v_cndmask_b32_e64 v59, 0, 32, vcc
	v_ldexp_f32 v31, v31, v59
	v_log_f32_e32 v31, v31
	v_cndmask_b32_e32 v59, 0, v231, vcc
	v_mul_f32_e32 v61, 0x3f317217, v31
	v_fma_f32 v61, v31, s0, -v61
	v_fmac_f32_e32 v61, 0x3377d1cf, v31
	v_fmac_f32_e32 v61, 0x3f317217, v31
	v_cmp_lt_f32_e64 vcc, |v31|, s1
	s_nop 1
	v_cndmask_b32_e32 v31, v31, v61, vcc
	v_sub_f32_e32 v31, v31, v59
	v_cndmask_b32_e64 v31, v31, v58, s[26:27]
	s_and_b64 vcc, exec, s[4:5]
	ds_write_b32 v35, v31 offset:48
	s_cbranch_vccnz .LBB0_295
	v_readlane_b32 s44, v253, 38
	v_mov_b32_e32 v31, v157
	v_readlane_b32 s52, v253, 46
	v_readlane_b32 s53, v253, 47
	s_movk_i32 s44, 0x90
	v_readlane_b32 s45, v253, 39
	v_lshl_add_u64 v[58:59], v[30:31], 2, s[52:53]
	v_readlane_b32 s46, v253, 40
	v_readlane_b32 s47, v253, 41
	v_readlane_b32 s48, v253, 42
	v_readlane_b32 s49, v253, 43
	v_readlane_b32 s50, v253, 44
	v_readlane_b32 s51, v253, 45
	v_readlane_b32 s54, v253, 48
	v_readlane_b32 s55, v253, 49
	v_readlane_b32 s56, v253, 50
	v_readlane_b32 s57, v253, 51
	v_readlane_b32 s58, v253, 52
	v_readlane_b32 s59, v253, 53
	s_waitcnt vmcnt(0)
	v_sub_f32_e32 v31, v127, v99
	v_mul_f32_e32 v31, 0xbfb8aa3b, v31
	v_exp_f32_e32 v31, v31
	s_nop 0
	v_add_f32_e32 v31, 1.0, v31
	v_rcp_f32_e32 v60, v31
; __device__ __forceinline__ float fexp(float x) { return __expf(x); }
; __device__ __forceinline__ float frcp(float x) { return __builtin_amdgcn_rcpf(x); }
; __device__ __forceinline__ float sigmoid_f(float x) { return frcp(1.0f + fexp(-x)); }
; __device__ __forceinline__ void hgrn_unit(const Ctx& X, LAS unsigned char* hl, int b, int c, int h, int tid_h, int w4, int lane, int layer) {
;     ...
;         for (int e = 0; e < 16; ++e) {
;             const int ch = h * 64 + ds + e;
;             const float lb = layer == 0 ? 0.f : sigmoid_f(X.in[12][256 + ch] - X.in[12][ch]);
;             const float f = ff[e];
;             const float ls = fminf(f, 0.f) - __logf(1.0f + fexp(-fabsf(f)));
;             const float lf = layer == 0 ? ls : __logf(lb + (1.f - lb) * fexp(ls));
;             kk[e] = (1.f - lb) * frcp(1.f + fexp(f));
;             Gt[i * 64 + ds + e] = lf;
;         }
.LBB0_295:
	v_and_b32_e32 v58, 0xffff0000, v24
	v_mul_f32_e64 v24, |v58|, s66
	v_exp_f32_e32 v24, v24
	s_nop 0
	v_add_f32_e32 v24, 1.0, v24
	v_cmp_gt_f32_e32 vcc, s3, v24
	s_nop 1
	v_cndmask_b32_e64 v31, 0, 32, vcc
	v_ldexp_f32 v24, v24, v31
	v_log_f32_e32 v24, v24
	v_cndmask_b32_e32 v59, 0, v231, vcc
	v_max_f32_e32 v31, v58, v58
	v_min_f32_e32 v31, 0, v31
	v_mul_f32_e32 v61, 0x3f317217, v24
	v_fma_f32 v61, v24, s6, -v61
	v_fmac_f32_e32 v61, 0x3377d1cf, v24
	v_fmac_f32_e32 v61, 0x3f317217, v24
	v_cmp_lt_f32_e64 vcc, |v24|, s7
	s_nop 1
	v_cndmask_b32_e32 v24, v24, v61, vcc
	v_sub_f32_e32 v24, v24, v59
	v_sub_f32_e32 v31, v31, v24
	v_mul_f32_e32 v24, 0x3fb8aa3b, v31
	v_exp_f32_e32 v24, v24
	v_sub_f32_e32 v59, 1.0, v60
	s_and_b64 vcc, exec, s[4:5]
	v_fmac_f32_e32 v60, v24, v59
	v_cmp_gt_f32_e64 s[0:1], s3, v60
	s_nop 1
	v_cndmask_b32_e64 v24, 0, 32, s[0:1]
	v_ldexp_f32 v24, v60, v24
	v_log_f32_e32 v60, v24
	v_cndmask_b32_e64 v61, 0, v231, s[0:1]
	v_mov_b32_e32 v24, 0
	v_mul_f32_e32 v62, 0x3f317217, v60
	v_fma_f32 v62, v60, s6, -v62
	v_fmac_f32_e32 v62, 0x3377d1cf, v60
	v_fmac_f32_e32 v62, 0x3f317217, v60
	v_cmp_lt_f32_e64 s[0:1], |v60|, s7
	s_nop 1
	v_cndmask_b32_e64 v60, v60, v62, s[0:1]
	v_sub_f32_e32 v60, v60, v61
	v_cndmask_b32_e64 v31, v60, v31, s[26:27]
	ds_write_b32 v35, v31 offset:52
	v_mov_b32_e32 v31, 0
	s_cbranch_vccnz .LBB0_297
	v_readlane_b32 s44, v253, 38
	v_mov_b32_e32 v31, v157
	v_readlane_b32 s52, v253, 46
	v_readlane_b32 s53, v253, 47
	s_movk_i32 s44, 0x90
	v_readlane_b32 s45, v253, 39
	v_lshl_add_u64 v[60:61], v[30:31], 2, s[52:53]
	v_readlane_b32 s46, v253, 40
	v_readlane_b32 s47, v253, 41
	v_readlane_b32 s48, v253, 42
	v_readlane_b32 s49, v253, 43
	v_readlane_b32 s50, v253, 44
	v_readlane_b32 s51, v253, 45
	v_readlane_b32 s54, v253, 48
	v_readlane_b32 s55, v253, 49
	v_readlane_b32 s56, v253, 50
	v_readlane_b32 s57, v253, 51
	v_readlane_b32 s58, v253, 52
	v_readlane_b32 s59, v253, 53
	s_waitcnt vmcnt(0)
	v_sub_f32_e32 v31, v128, v100
	v_mul_f32_e32 v31, 0xbfb8aa3b, v31
	v_exp_f32_e32 v31, v31
	s_nop 0
	v_add_f32_e32 v31, 1.0, v31
	v_rcp_f32_e32 v31, v31
.LBB0_297:
	v_lshlrev_b32_e32 v62, 16, v25
	v_mul_f32_e64 v60, |v62|, s66
	v_exp_f32_e32 v60, v60
	s_mov_b32 s0, 0x3f317217
	s_mov_b32 s1, 0x7f800000
	v_sub_f32_e32 v76, 1.0, v31
	v_add_f32_e32 v60, 1.0, v60
	v_cmp_gt_f32_e32 vcc, s3, v60
	s_nop 1
	v_cndmask_b32_e64 v61, 0, 32, vcc
	v_ldexp_f32 v60, v60, v61
	v_log_f32_e32 v60, v60
	v_cndmask_b32_e32 v63, 0, v231, vcc
	v_max_f32_e32 v61, v62, v62
	v_min_f32_e32 v61, 0, v61
	v_mul_f32_e32 v64, 0x3f317217, v60
	v_fma_f32 v64, v60, s0, -v64
	v_fmac_f32_e32 v64, 0x3377d1cf, v60
	v_fmac_f32_e32 v64, 0x3f317217, v60
	v_cmp_lt_f32_e64 vcc, |v60|, s1
	s_nop 1
	v_cndmask_b32_e32 v60, v60, v64, vcc
	v_sub_f32_e32 v60, v60, v63
	v_sub_f32_e32 v60, v61, v60
	v_mul_f32_e32 v61, 0x3fb8aa3b, v60
	v_exp_f32_e32 v61, v61
	s_nop 0
	v_fmac_f32_e32 v31, v61, v76
	v_cmp_gt_f32_e32 vcc, s3, v31
	s_nop 1
	v_cndmask_b32_e64 v61, 0, 32, vcc
	v_ldexp_f32 v31, v31, v61
	v_log_f32_e32 v31, v31
	v_cndmask_b32_e32 v61, 0, v231, vcc
	v_mul_f32_e32 v63, 0x3f317217, v31
	v_fma_f32 v63, v31, s0, -v63
	v_fmac_f32_e32 v63, 0x3377d1cf, v31
	v_fmac_f32_e32 v63, 0x3f317217, v31
	v_cmp_lt_f32_e64 vcc, |v31|, s1
	s_nop 1
	v_cndmask_b32_e32 v31, v31, v63, vcc
	v_sub_f32_e32 v31, v31, v61
	v_cndmask_b32_e64 v31, v31, v60, s[26:27]
	s_and_b64 vcc, exec, s[4:5]
	ds_write_b32 v35, v31 offset:56
	s_cbranch_vccnz .LBB0_299
	v_readlane_b32 s44, v253, 38
	v_mov_b32_e32 v31, v157
	v_readlane_b32 s52, v253, 46
	v_readlane_b32 s53, v253, 47
	s_movk_i32 s44, 0x90
	v_readlane_b32 s45, v253, 39
	v_lshl_add_u64 v[30:31], v[30:31], 2, s[52:53]
	v_readlane_b32 s46, v253, 40
	v_readlane_b32 s47, v253, 41
	v_readlane_b32 s48, v253, 42
	v_readlane_b32 s49, v253, 43
	v_readlane_b32 s50, v253, 44
	v_readlane_b32 s51, v253, 45
	v_readlane_b32 s54, v253, 48
	v_readlane_b32 s55, v253, 49
	v_readlane_b32 s56, v253, 50
	v_readlane_b32 s57, v253, 51
	v_readlane_b32 s58, v253, 52
	v_readlane_b32 s59, v253, 53
	s_waitcnt vmcnt(0)
	v_sub_f32_e32 v24, v129, v101
	v_mul_f32_e32 v24, 0xbfb8aa3b, v24
	v_exp_f32_e32 v24, v24
	s_nop 0
	v_add_f32_e32 v24, 1.0, v24
	v_rcp_f32_e32 v24, v24
